# phase 0 GEMV job prologue: 24 conditioning-vector loads per thread issued together with counted waits (was load-wait-silu-store x24)
# speedup vs baseline: 1.0063x; 1.0063x over previous
.LBB0_41:
	s_andn2_b64 vcc, exec, s[0:1]
	s_cbranch_vccnz .LBB0_22
	v_readlane_b32 s64, v254, 44
	v_readlane_b32 s65, v254, 45
	v_readlane_b32 s66, v254, 46
	v_readlane_b32 s67, v254, 47
	v_readlane_b32 s68, v254, 48
	v_readlane_b32 s69, v254, 49
	v_readlane_b32 s70, v254, 50
	v_readlane_b32 s71, v254, 51
	v_readlane_b32 s72, v254, 52
	v_readlane_b32 s73, v254, 53
	v_readlane_b32 s74, v254, 54
	v_readlane_b32 s75, v254, 55
	v_readlane_b32 s76, v254, 56
	v_readlane_b32 s77, v254, 57
	v_readlane_b32 s78, v254, 58
	v_readlane_b32 s79, v254, 59
	s_mov_b64 s[2:3], s[66:67]
	v_readlane_b32 s64, v254, 28
	v_mov_b32_e32 v15, v180
	v_readlane_b32 s68, v254, 32
	v_readlane_b32 s69, v254, 33
	s_mov_b64 s[4:5], s[68:69]
	v_cmp_gt_i32_e32 vcc, s60, v15
	v_readlane_b32 s65, v254, 29
	v_readlane_b32 s66, v254, 30
	v_readlane_b32 s67, v254, 31
	v_readlane_b32 s70, v254, 34
	v_readlane_b32 s71, v254, 35
	v_readlane_b32 s72, v254, 36
	v_readlane_b32 s73, v254, 37
	v_readlane_b32 s74, v254, 38
	v_readlane_b32 s75, v254, 39
	v_readlane_b32 s76, v254, 40
	v_readlane_b32 s77, v254, 41
	v_readlane_b32 s78, v254, 42
	v_readlane_b32 s79, v254, 43
	s_and_saveexec_b64 s[6:7], vcc
	s_cbranch_execz .LBB0_49
	v_lshl_add_u32 v2, v15, 2, 0
	v_lshlrev_b32_e32 v9, 2, v15
	global_load_dword v64, v9, s[2:3]
	global_load_dword v65, v9, s[2:3] offset:2048
	v_add_u32_e32 v10, 0x1000, v9
	global_load_dword v66, v10, s[2:3]
	v_add_u32_e32 v10, 0x1800, v9
	global_load_dword v67, v10, s[2:3]
	v_add_u32_e32 v10, 0x2000, v9
	global_load_dword v68, v10, s[2:3]
	v_add_u32_e32 v10, 0x2800, v9
	global_load_dword v69, v10, s[2:3]
	v_add_u32_e32 v10, 0x3000, v9
	global_load_dword v70, v10, s[2:3]
	v_add_u32_e32 v10, 0x3800, v9
	global_load_dword v71, v10, s[2:3]
	global_load_dword v72, v9, s[4:5]
	global_load_dword v73, v9, s[4:5] offset:2048
	v_add_u32_e32 v10, 0x1000, v9
	global_load_dword v74, v10, s[4:5]
	v_add_u32_e32 v10, 0x1800, v9
	global_load_dword v75, v10, s[4:5]
	v_add_u32_e32 v10, 0x2000, v9
	global_load_dword v76, v10, s[4:5]
	v_add_u32_e32 v10, 0x2800, v9
	global_load_dword v77, v10, s[4:5]
	v_add_u32_e32 v10, 0x3000, v9
	global_load_dword v78, v10, s[4:5]
	v_add_u32_e32 v10, 0x3800, v9
	global_load_dword v79, v10, s[4:5]
	v_add_u32_e32 v10, 0x4000, v9
	global_load_dword v80, v10, s[4:5]
	v_add_u32_e32 v10, 0x4800, v9
	global_load_dword v81, v10, s[4:5]
	v_add_u32_e32 v10, 0x5000, v9
	global_load_dword v82, v10, s[4:5]
	v_add_u32_e32 v10, 0x5800, v9
	global_load_dword v83, v10, s[4:5]
	v_add_u32_e32 v10, 0x6000, v9
	global_load_dword v84, v10, s[4:5]
	v_add_u32_e32 v10, 0x6800, v9
	global_load_dword v85, v10, s[4:5]
	v_add_u32_e32 v10, 0x7000, v9
	global_load_dword v86, v10, s[4:5]
	v_add_u32_e32 v10, 0x7800, v9
	global_load_dword v87, v10, s[4:5]
	s_waitcnt vmcnt(23)
	v_mov_b32_e32 v0, v64
	v_mul_f32_e32 v1, 0xbfb8aa3b, v0
	v_rndne_f32_e32 v4, v1
	v_fma_f32 v5, v0, s57, -v1
	v_sub_f32_e32 v1, v1, v4
	v_fmac_f32_e32 v5, 0xb2a5705f, v0
	v_add_f32_e32 v1, v1, v5
	v_cvt_i32_f32_e32 v4, v4
	v_exp_f32_e32 v1, v1
	v_cmp_nlt_f32_e64 s[0:1], s58, v0
	s_nop 0
	v_ldexp_f32 v1, v1, v4
	v_cndmask_b32_e64 v1, 0, v1, s[0:1]
	v_cmp_ngt_f32_e64 s[0:1], s59, v0
	s_nop 1
	v_cndmask_b32_e64 v1, v42, v1, s[0:1]
	v_add_f32_e32 v1, 1.0, v1
	v_div_scale_f32 v3, s[0:1], v1, v1, v0
	v_rcp_f32_e32 v4, v3
	v_div_scale_f32 v6, vcc, v0, v1, v0
	v_fma_f32 v7, -v3, v4, 1.0
	v_fmac_f32_e32 v4, v7, v4
	v_mul_f32_e32 v7, v6, v4
	v_fma_f32 v8, -v3, v7, v6
	v_fmac_f32_e32 v7, v8, v4
	v_fma_f32 v3, -v3, v7, v6
	v_div_fmas_f32 v3, v3, v4, v7
	v_div_fixup_f32 v0, v3, v1, v0
	ds_write_b32 v2, v0
	v_add_u32_e32 v2, 0x800, v2
	s_waitcnt vmcnt(22)
	v_mov_b32_e32 v0, v65
	v_mul_f32_e32 v1, 0xbfb8aa3b, v0
	v_rndne_f32_e32 v4, v1
	v_fma_f32 v5, v0, s57, -v1
	v_sub_f32_e32 v1, v1, v4
	v_fmac_f32_e32 v5, 0xb2a5705f, v0
	v_add_f32_e32 v1, v1, v5
	v_cvt_i32_f32_e32 v4, v4
	v_exp_f32_e32 v1, v1
	v_cmp_nlt_f32_e64 s[0:1], s58, v0
	s_nop 0
	v_ldexp_f32 v1, v1, v4
	v_cndmask_b32_e64 v1, 0, v1, s[0:1]
	v_cmp_ngt_f32_e64 s[0:1], s59, v0
	s_nop 1
	v_cndmask_b32_e64 v1, v42, v1, s[0:1]
	v_add_f32_e32 v1, 1.0, v1
	v_div_scale_f32 v3, s[0:1], v1, v1, v0
	v_rcp_f32_e32 v4, v3
	v_div_scale_f32 v6, vcc, v0, v1, v0
	v_fma_f32 v7, -v3, v4, 1.0
	v_fmac_f32_e32 v4, v7, v4
	v_mul_f32_e32 v7, v6, v4
	v_fma_f32 v8, -v3, v7, v6
	v_fmac_f32_e32 v7, v8, v4
	v_fma_f32 v3, -v3, v7, v6
	v_div_fmas_f32 v3, v3, v4, v7
	v_div_fixup_f32 v0, v3, v1, v0
	ds_write_b32 v2, v0
	v_add_u32_e32 v2, 0x800, v2
	s_waitcnt vmcnt(21)
	v_mov_b32_e32 v0, v66
	v_mul_f32_e32 v1, 0xbfb8aa3b, v0
	v_rndne_f32_e32 v4, v1
	v_fma_f32 v5, v0, s57, -v1
	v_sub_f32_e32 v1, v1, v4
	v_fmac_f32_e32 v5, 0xb2a5705f, v0
	v_add_f32_e32 v1, v1, v5
	v_cvt_i32_f32_e32 v4, v4
	v_exp_f32_e32 v1, v1
	v_cmp_nlt_f32_e64 s[0:1], s58, v0
	s_nop 0
	v_ldexp_f32 v1, v1, v4
	v_cndmask_b32_e64 v1, 0, v1, s[0:1]
	v_cmp_ngt_f32_e64 s[0:1], s59, v0
	s_nop 1
	v_cndmask_b32_e64 v1, v42, v1, s[0:1]
	v_add_f32_e32 v1, 1.0, v1
	v_div_scale_f32 v3, s[0:1], v1, v1, v0
	v_rcp_f32_e32 v4, v3
	v_div_scale_f32 v6, vcc, v0, v1, v0
	v_fma_f32 v7, -v3, v4, 1.0
	v_fmac_f32_e32 v4, v7, v4
	v_mul_f32_e32 v7, v6, v4
	v_fma_f32 v8, -v3, v7, v6
	v_fmac_f32_e32 v7, v8, v4
	v_fma_f32 v3, -v3, v7, v6
	v_div_fmas_f32 v3, v3, v4, v7
	v_div_fixup_f32 v0, v3, v1, v0
	ds_write_b32 v2, v0
	v_add_u32_e32 v2, 0x800, v2
	s_waitcnt vmcnt(20)
	v_mov_b32_e32 v0, v67
	v_mul_f32_e32 v1, 0xbfb8aa3b, v0
	v_rndne_f32_e32 v4, v1
	v_fma_f32 v5, v0, s57, -v1
	v_sub_f32_e32 v1, v1, v4
	v_fmac_f32_e32 v5, 0xb2a5705f, v0
	v_add_f32_e32 v1, v1, v5
	v_cvt_i32_f32_e32 v4, v4
	v_exp_f32_e32 v1, v1
	v_cmp_nlt_f32_e64 s[0:1], s58, v0
	s_nop 0
	v_ldexp_f32 v1, v1, v4
	v_cndmask_b32_e64 v1, 0, v1, s[0:1]
	v_cmp_ngt_f32_e64 s[0:1], s59, v0
	s_nop 1
	v_cndmask_b32_e64 v1, v42, v1, s[0:1]
	v_add_f32_e32 v1, 1.0, v1
	v_div_scale_f32 v3, s[0:1], v1, v1, v0
	v_rcp_f32_e32 v4, v3
	v_div_scale_f32 v6, vcc, v0, v1, v0
	v_fma_f32 v7, -v3, v4, 1.0
	v_fmac_f32_e32 v4, v7, v4
	v_mul_f32_e32 v7, v6, v4
	v_fma_f32 v8, -v3, v7, v6
	v_fmac_f32_e32 v7, v8, v4
	v_fma_f32 v3, -v3, v7, v6
	v_div_fmas_f32 v3, v3, v4, v7
	v_div_fixup_f32 v0, v3, v1, v0
	ds_write_b32 v2, v0
	v_add_u32_e32 v2, 0x800, v2
	s_waitcnt vmcnt(19)
	v_mov_b32_e32 v0, v68
	v_mul_f32_e32 v1, 0xbfb8aa3b, v0
	v_rndne_f32_e32 v4, v1
	v_fma_f32 v5, v0, s57, -v1
	v_sub_f32_e32 v1, v1, v4
	v_fmac_f32_e32 v5, 0xb2a5705f, v0
	v_add_f32_e32 v1, v1, v5
	v_cvt_i32_f32_e32 v4, v4
	v_exp_f32_e32 v1, v1
	v_cmp_nlt_f32_e64 s[0:1], s58, v0
	s_nop 0
	v_ldexp_f32 v1, v1, v4
	v_cndmask_b32_e64 v1, 0, v1, s[0:1]
	v_cmp_ngt_f32_e64 s[0:1], s59, v0
	s_nop 1
	v_cndmask_b32_e64 v1, v42, v1, s[0:1]
	v_add_f32_e32 v1, 1.0, v1
	v_div_scale_f32 v3, s[0:1], v1, v1, v0
	v_rcp_f32_e32 v4, v3
	v_div_scale_f32 v6, vcc, v0, v1, v0
	v_fma_f32 v7, -v3, v4, 1.0
	v_fmac_f32_e32 v4, v7, v4
	v_mul_f32_e32 v7, v6, v4
	v_fma_f32 v8, -v3, v7, v6
	v_fmac_f32_e32 v7, v8, v4
	v_fma_f32 v3, -v3, v7, v6
	v_div_fmas_f32 v3, v3, v4, v7
	v_div_fixup_f32 v0, v3, v1, v0
	ds_write_b32 v2, v0
	v_add_u32_e32 v2, 0x800, v2
	s_waitcnt vmcnt(18)
	v_mov_b32_e32 v0, v69
	v_mul_f32_e32 v1, 0xbfb8aa3b, v0
	v_rndne_f32_e32 v4, v1
	v_fma_f32 v5, v0, s57, -v1
	v_sub_f32_e32 v1, v1, v4
	v_fmac_f32_e32 v5, 0xb2a5705f, v0
	v_add_f32_e32 v1, v1, v5
	v_cvt_i32_f32_e32 v4, v4
	v_exp_f32_e32 v1, v1
	v_cmp_nlt_f32_e64 s[0:1], s58, v0
	s_nop 0
	v_ldexp_f32 v1, v1, v4
	v_cndmask_b32_e64 v1, 0, v1, s[0:1]
	v_cmp_ngt_f32_e64 s[0:1], s59, v0
	s_nop 1
	v_cndmask_b32_e64 v1, v42, v1, s[0:1]
	v_add_f32_e32 v1, 1.0, v1
	v_div_scale_f32 v3, s[0:1], v1, v1, v0
	v_rcp_f32_e32 v4, v3
	v_div_scale_f32 v6, vcc, v0, v1, v0
	v_fma_f32 v7, -v3, v4, 1.0
	v_fmac_f32_e32 v4, v7, v4
	v_mul_f32_e32 v7, v6, v4
	v_fma_f32 v8, -v3, v7, v6
	v_fmac_f32_e32 v7, v8, v4
	v_fma_f32 v3, -v3, v7, v6
	v_div_fmas_f32 v3, v3, v4, v7
	v_div_fixup_f32 v0, v3, v1, v0
	ds_write_b32 v2, v0
	v_add_u32_e32 v2, 0x800, v2
	s_waitcnt vmcnt(17)
	v_mov_b32_e32 v0, v70
	v_mul_f32_e32 v1, 0xbfb8aa3b, v0
	v_rndne_f32_e32 v4, v1
	v_fma_f32 v5, v0, s57, -v1
	v_sub_f32_e32 v1, v1, v4
	v_fmac_f32_e32 v5, 0xb2a5705f, v0
	v_add_f32_e32 v1, v1, v5
	v_cvt_i32_f32_e32 v4, v4
	v_exp_f32_e32 v1, v1
	v_cmp_nlt_f32_e64 s[0:1], s58, v0
	s_nop 0
	v_ldexp_f32 v1, v1, v4
	v_cndmask_b32_e64 v1, 0, v1, s[0:1]
	v_cmp_ngt_f32_e64 s[0:1], s59, v0
	s_nop 1
	v_cndmask_b32_e64 v1, v42, v1, s[0:1]
	v_add_f32_e32 v1, 1.0, v1
	v_div_scale_f32 v3, s[0:1], v1, v1, v0
	v_rcp_f32_e32 v4, v3
	v_div_scale_f32 v6, vcc, v0, v1, v0
	v_fma_f32 v7, -v3, v4, 1.0
	v_fmac_f32_e32 v4, v7, v4
	v_mul_f32_e32 v7, v6, v4
	v_fma_f32 v8, -v3, v7, v6
	v_fmac_f32_e32 v7, v8, v4
	v_fma_f32 v3, -v3, v7, v6
	v_div_fmas_f32 v3, v3, v4, v7
	v_div_fixup_f32 v0, v3, v1, v0
	ds_write_b32 v2, v0
	v_add_u32_e32 v2, 0x800, v2
	s_waitcnt vmcnt(16)
	v_mov_b32_e32 v0, v71
	v_mul_f32_e32 v1, 0xbfb8aa3b, v0
	v_rndne_f32_e32 v4, v1
	v_fma_f32 v5, v0, s57, -v1
	v_sub_f32_e32 v1, v1, v4
	v_fmac_f32_e32 v5, 0xb2a5705f, v0
	v_add_f32_e32 v1, v1, v5
	v_cvt_i32_f32_e32 v4, v4
	v_exp_f32_e32 v1, v1
	v_cmp_nlt_f32_e64 s[0:1], s58, v0
	s_nop 0
	v_ldexp_f32 v1, v1, v4
	v_cndmask_b32_e64 v1, 0, v1, s[0:1]
	v_cmp_ngt_f32_e64 s[0:1], s59, v0
	s_nop 1
	v_cndmask_b32_e64 v1, v42, v1, s[0:1]
	v_add_f32_e32 v1, 1.0, v1
	v_div_scale_f32 v3, s[0:1], v1, v1, v0
	v_rcp_f32_e32 v4, v3
	v_div_scale_f32 v6, vcc, v0, v1, v0
	v_fma_f32 v7, -v3, v4, 1.0
	v_fmac_f32_e32 v4, v7, v4
	v_mul_f32_e32 v7, v6, v4
	v_fma_f32 v8, -v3, v7, v6
	v_fmac_f32_e32 v7, v8, v4
	v_fma_f32 v3, -v3, v7, v6
	v_div_fmas_f32 v3, v3, v4, v7
	v_div_fixup_f32 v0, v3, v1, v0
	ds_write_b32 v2, v0
	v_add_u32_e32 v2, 0x800, v2
	s_waitcnt vmcnt(15)
	v_mov_b32_e32 v0, v72
	v_mul_f32_e32 v1, 0xbfb8aa3b, v0
	v_rndne_f32_e32 v4, v1
	v_fma_f32 v5, v0, s57, -v1
	v_sub_f32_e32 v1, v1, v4
	v_fmac_f32_e32 v5, 0xb2a5705f, v0
	v_add_f32_e32 v1, v1, v5
	v_cvt_i32_f32_e32 v4, v4
	v_exp_f32_e32 v1, v1
	v_cmp_nlt_f32_e64 s[0:1], s58, v0
	s_nop 0
	v_ldexp_f32 v1, v1, v4
	v_cndmask_b32_e64 v1, 0, v1, s[0:1]
	v_cmp_ngt_f32_e64 s[0:1], s59, v0
	s_nop 1
	v_cndmask_b32_e64 v1, v42, v1, s[0:1]
	v_add_f32_e32 v1, 1.0, v1
	v_div_scale_f32 v3, s[0:1], v1, v1, v0
	v_rcp_f32_e32 v4, v3
	v_div_scale_f32 v6, vcc, v0, v1, v0
	v_fma_f32 v7, -v3, v4, 1.0
	v_fmac_f32_e32 v4, v7, v4
	v_mul_f32_e32 v7, v6, v4
	v_fma_f32 v8, -v3, v7, v6
	v_fmac_f32_e32 v7, v8, v4
	v_fma_f32 v3, -v3, v7, v6
	v_div_fmas_f32 v3, v3, v4, v7
	v_div_fixup_f32 v0, v3, v1, v0
	ds_write_b32 v2, v0
	v_add_u32_e32 v2, 0x800, v2
	s_waitcnt vmcnt(14)
	v_mov_b32_e32 v0, v73
	v_mul_f32_e32 v1, 0xbfb8aa3b, v0
	v_rndne_f32_e32 v4, v1
	v_fma_f32 v5, v0, s57, -v1
	v_sub_f32_e32 v1, v1, v4
	v_fmac_f32_e32 v5, 0xb2a5705f, v0
	v_add_f32_e32 v1, v1, v5
	v_cvt_i32_f32_e32 v4, v4
	v_exp_f32_e32 v1, v1
	v_cmp_nlt_f32_e64 s[0:1], s58, v0
	s_nop 0
	v_ldexp_f32 v1, v1, v4
	v_cndmask_b32_e64 v1, 0, v1, s[0:1]
	v_cmp_ngt_f32_e64 s[0:1], s59, v0
	s_nop 1
	v_cndmask_b32_e64 v1, v42, v1, s[0:1]
	v_add_f32_e32 v1, 1.0, v1
	v_div_scale_f32 v3, s[0:1], v1, v1, v0
	v_rcp_f32_e32 v4, v3
	v_div_scale_f32 v6, vcc, v0, v1, v0
	v_fma_f32 v7, -v3, v4, 1.0
	v_fmac_f32_e32 v4, v7, v4
	v_mul_f32_e32 v7, v6, v4
	v_fma_f32 v8, -v3, v7, v6
	v_fmac_f32_e32 v7, v8, v4
	v_fma_f32 v3, -v3, v7, v6
	v_div_fmas_f32 v3, v3, v4, v7
	v_div_fixup_f32 v0, v3, v1, v0
	ds_write_b32 v2, v0
	v_add_u32_e32 v2, 0x800, v2
	s_waitcnt vmcnt(13)
	v_mov_b32_e32 v0, v74
	v_mul_f32_e32 v1, 0xbfb8aa3b, v0
	v_rndne_f32_e32 v4, v1
	v_fma_f32 v5, v0, s57, -v1
	v_sub_f32_e32 v1, v1, v4
	v_fmac_f32_e32 v5, 0xb2a5705f, v0
	v_add_f32_e32 v1, v1, v5
	v_cvt_i32_f32_e32 v4, v4
	v_exp_f32_e32 v1, v1
	v_cmp_nlt_f32_e64 s[0:1], s58, v0
	s_nop 0
	v_ldexp_f32 v1, v1, v4
	v_cndmask_b32_e64 v1, 0, v1, s[0:1]
	v_cmp_ngt_f32_e64 s[0:1], s59, v0
	s_nop 1
	v_cndmask_b32_e64 v1, v42, v1, s[0:1]
	v_add_f32_e32 v1, 1.0, v1
	v_div_scale_f32 v3, s[0:1], v1, v1, v0
	v_rcp_f32_e32 v4, v3
	v_div_scale_f32 v6, vcc, v0, v1, v0
	v_fma_f32 v7, -v3, v4, 1.0
	v_fmac_f32_e32 v4, v7, v4
	v_mul_f32_e32 v7, v6, v4
	v_fma_f32 v8, -v3, v7, v6
	v_fmac_f32_e32 v7, v8, v4
	v_fma_f32 v3, -v3, v7, v6
	v_div_fmas_f32 v3, v3, v4, v7
	v_div_fixup_f32 v0, v3, v1, v0
	ds_write_b32 v2, v0
	v_add_u32_e32 v2, 0x800, v2
	s_waitcnt vmcnt(12)
	v_mov_b32_e32 v0, v75
	v_mul_f32_e32 v1, 0xbfb8aa3b, v0
	v_rndne_f32_e32 v4, v1
	v_fma_f32 v5, v0, s57, -v1
	v_sub_f32_e32 v1, v1, v4
	v_fmac_f32_e32 v5, 0xb2a5705f, v0
	v_add_f32_e32 v1, v1, v5
	v_cvt_i32_f32_e32 v4, v4
	v_exp_f32_e32 v1, v1
	v_cmp_nlt_f32_e64 s[0:1], s58, v0
	s_nop 0
	v_ldexp_f32 v1, v1, v4
	v_cndmask_b32_e64 v1, 0, v1, s[0:1]
	v_cmp_ngt_f32_e64 s[0:1], s59, v0
	s_nop 1
	v_cndmask_b32_e64 v1, v42, v1, s[0:1]
	v_add_f32_e32 v1, 1.0, v1
	v_div_scale_f32 v3, s[0:1], v1, v1, v0
	v_rcp_f32_e32 v4, v3
	v_div_scale_f32 v6, vcc, v0, v1, v0
	v_fma_f32 v7, -v3, v4, 1.0
	v_fmac_f32_e32 v4, v7, v4
	v_mul_f32_e32 v7, v6, v4
	v_fma_f32 v8, -v3, v7, v6
	v_fmac_f32_e32 v7, v8, v4
	v_fma_f32 v3, -v3, v7, v6
	v_div_fmas_f32 v3, v3, v4, v7
	v_div_fixup_f32 v0, v3, v1, v0
	ds_write_b32 v2, v0
	v_add_u32_e32 v2, 0x800, v2
	s_waitcnt vmcnt(11)
	v_mov_b32_e32 v0, v76
	v_mul_f32_e32 v1, 0xbfb8aa3b, v0
	v_rndne_f32_e32 v4, v1
	v_fma_f32 v5, v0, s57, -v1
	v_sub_f32_e32 v1, v1, v4
	v_fmac_f32_e32 v5, 0xb2a5705f, v0
	v_add_f32_e32 v1, v1, v5
	v_cvt_i32_f32_e32 v4, v4
	v_exp_f32_e32 v1, v1
	v_cmp_nlt_f32_e64 s[0:1], s58, v0
	s_nop 0
	v_ldexp_f32 v1, v1, v4
	v_cndmask_b32_e64 v1, 0, v1, s[0:1]
	v_cmp_ngt_f32_e64 s[0:1], s59, v0
	s_nop 1
	v_cndmask_b32_e64 v1, v42, v1, s[0:1]
	v_add_f32_e32 v1, 1.0, v1
	v_div_scale_f32 v3, s[0:1], v1, v1, v0
	v_rcp_f32_e32 v4, v3
	v_div_scale_f32 v6, vcc, v0, v1, v0
	v_fma_f32 v7, -v3, v4, 1.0
	v_fmac_f32_e32 v4, v7, v4
	v_mul_f32_e32 v7, v6, v4
	v_fma_f32 v8, -v3, v7, v6
	v_fmac_f32_e32 v7, v8, v4
	v_fma_f32 v3, -v3, v7, v6
	v_div_fmas_f32 v3, v3, v4, v7
	v_div_fixup_f32 v0, v3, v1, v0
	ds_write_b32 v2, v0
	v_add_u32_e32 v2, 0x800, v2
	s_waitcnt vmcnt(10)
	v_mov_b32_e32 v0, v77
	v_mul_f32_e32 v1, 0xbfb8aa3b, v0
	v_rndne_f32_e32 v4, v1
	v_fma_f32 v5, v0, s57, -v1
	v_sub_f32_e32 v1, v1, v4
	v_fmac_f32_e32 v5, 0xb2a5705f, v0
	v_add_f32_e32 v1, v1, v5
	v_cvt_i32_f32_e32 v4, v4
	v_exp_f32_e32 v1, v1
	v_cmp_nlt_f32_e64 s[0:1], s58, v0
	s_nop 0
	v_ldexp_f32 v1, v1, v4
	v_cndmask_b32_e64 v1, 0, v1, s[0:1]
	v_cmp_ngt_f32_e64 s[0:1], s59, v0
	s_nop 1
	v_cndmask_b32_e64 v1, v42, v1, s[0:1]
	v_add_f32_e32 v1, 1.0, v1
	v_div_scale_f32 v3, s[0:1], v1, v1, v0
	v_rcp_f32_e32 v4, v3
	v_div_scale_f32 v6, vcc, v0, v1, v0
	v_fma_f32 v7, -v3, v4, 1.0
	v_fmac_f32_e32 v4, v7, v4
	v_mul_f32_e32 v7, v6, v4
	v_fma_f32 v8, -v3, v7, v6
	v_fmac_f32_e32 v7, v8, v4
	v_fma_f32 v3, -v3, v7, v6
	v_div_fmas_f32 v3, v3, v4, v7
	v_div_fixup_f32 v0, v3, v1, v0
	ds_write_b32 v2, v0
	v_add_u32_e32 v2, 0x800, v2
	s_waitcnt vmcnt(9)
	v_mov_b32_e32 v0, v78
	v_mul_f32_e32 v1, 0xbfb8aa3b, v0
	v_rndne_f32_e32 v4, v1
	v_fma_f32 v5, v0, s57, -v1
	v_sub_f32_e32 v1, v1, v4
	v_fmac_f32_e32 v5, 0xb2a5705f, v0
	v_add_f32_e32 v1, v1, v5
	v_cvt_i32_f32_e32 v4, v4
	v_exp_f32_e32 v1, v1
	v_cmp_nlt_f32_e64 s[0:1], s58, v0
	s_nop 0
	v_ldexp_f32 v1, v1, v4
	v_cndmask_b32_e64 v1, 0, v1, s[0:1]
	v_cmp_ngt_f32_e64 s[0:1], s59, v0
	s_nop 1
	v_cndmask_b32_e64 v1, v42, v1, s[0:1]
	v_add_f32_e32 v1, 1.0, v1
	v_div_scale_f32 v3, s[0:1], v1, v1, v0
	v_rcp_f32_e32 v4, v3
	v_div_scale_f32 v6, vcc, v0, v1, v0
	v_fma_f32 v7, -v3, v4, 1.0
	v_fmac_f32_e32 v4, v7, v4
	v_mul_f32_e32 v7, v6, v4
	v_fma_f32 v8, -v3, v7, v6
	v_fmac_f32_e32 v7, v8, v4
	v_fma_f32 v3, -v3, v7, v6
	v_div_fmas_f32 v3, v3, v4, v7
	v_div_fixup_f32 v0, v3, v1, v0
	ds_write_b32 v2, v0
	v_add_u32_e32 v2, 0x800, v2
	s_waitcnt vmcnt(8)
	v_mov_b32_e32 v0, v79
	v_mul_f32_e32 v1, 0xbfb8aa3b, v0
	v_rndne_f32_e32 v4, v1
	v_fma_f32 v5, v0, s57, -v1
	v_sub_f32_e32 v1, v1, v4
	v_fmac_f32_e32 v5, 0xb2a5705f, v0
	v_add_f32_e32 v1, v1, v5
	v_cvt_i32_f32_e32 v4, v4
	v_exp_f32_e32 v1, v1
	v_cmp_nlt_f32_e64 s[0:1], s58, v0
	s_nop 0
	v_ldexp_f32 v1, v1, v4
	v_cndmask_b32_e64 v1, 0, v1, s[0:1]
	v_cmp_ngt_f32_e64 s[0:1], s59, v0
	s_nop 1
	v_cndmask_b32_e64 v1, v42, v1, s[0:1]
	v_add_f32_e32 v1, 1.0, v1
	v_div_scale_f32 v3, s[0:1], v1, v1, v0
	v_rcp_f32_e32 v4, v3
	v_div_scale_f32 v6, vcc, v0, v1, v0
	v_fma_f32 v7, -v3, v4, 1.0
	v_fmac_f32_e32 v4, v7, v4
	v_mul_f32_e32 v7, v6, v4
	v_fma_f32 v8, -v3, v7, v6
	v_fmac_f32_e32 v7, v8, v4
	v_fma_f32 v3, -v3, v7, v6
	v_div_fmas_f32 v3, v3, v4, v7
	v_div_fixup_f32 v0, v3, v1, v0
	ds_write_b32 v2, v0
	v_add_u32_e32 v2, 0x800, v2
	s_waitcnt vmcnt(7)
	v_mov_b32_e32 v0, v80
	v_mul_f32_e32 v1, 0xbfb8aa3b, v0
	v_rndne_f32_e32 v4, v1
	v_fma_f32 v5, v0, s57, -v1
	v_sub_f32_e32 v1, v1, v4
	v_fmac_f32_e32 v5, 0xb2a5705f, v0
	v_add_f32_e32 v1, v1, v5
	v_cvt_i32_f32_e32 v4, v4
	v_exp_f32_e32 v1, v1
	v_cmp_nlt_f32_e64 s[0:1], s58, v0
	s_nop 0
	v_ldexp_f32 v1, v1, v4
	v_cndmask_b32_e64 v1, 0, v1, s[0:1]
	v_cmp_ngt_f32_e64 s[0:1], s59, v0
	s_nop 1
	v_cndmask_b32_e64 v1, v42, v1, s[0:1]
	v_add_f32_e32 v1, 1.0, v1
	v_div_scale_f32 v3, s[0:1], v1, v1, v0
	v_rcp_f32_e32 v4, v3
	v_div_scale_f32 v6, vcc, v0, v1, v0
	v_fma_f32 v7, -v3, v4, 1.0
	v_fmac_f32_e32 v4, v7, v4
	v_mul_f32_e32 v7, v6, v4
	v_fma_f32 v8, -v3, v7, v6
	v_fmac_f32_e32 v7, v8, v4
	v_fma_f32 v3, -v3, v7, v6
	v_div_fmas_f32 v3, v3, v4, v7
	v_div_fixup_f32 v0, v3, v1, v0
	ds_write_b32 v2, v0
	v_add_u32_e32 v2, 0x800, v2
	s_waitcnt vmcnt(6)
	v_mov_b32_e32 v0, v81
	v_mul_f32_e32 v1, 0xbfb8aa3b, v0
	v_rndne_f32_e32 v4, v1
	v_fma_f32 v5, v0, s57, -v1
	v_sub_f32_e32 v1, v1, v4
	v_fmac_f32_e32 v5, 0xb2a5705f, v0
	v_add_f32_e32 v1, v1, v5
	v_cvt_i32_f32_e32 v4, v4
	v_exp_f32_e32 v1, v1
	v_cmp_nlt_f32_e64 s[0:1], s58, v0
	s_nop 0
	v_ldexp_f32 v1, v1, v4
	v_cndmask_b32_e64 v1, 0, v1, s[0:1]
	v_cmp_ngt_f32_e64 s[0:1], s59, v0
	s_nop 1
	v_cndmask_b32_e64 v1, v42, v1, s[0:1]
	v_add_f32_e32 v1, 1.0, v1
	v_div_scale_f32 v3, s[0:1], v1, v1, v0
	v_rcp_f32_e32 v4, v3
	v_div_scale_f32 v6, vcc, v0, v1, v0
	v_fma_f32 v7, -v3, v4, 1.0
	v_fmac_f32_e32 v4, v7, v4
	v_mul_f32_e32 v7, v6, v4
	v_fma_f32 v8, -v3, v7, v6
	v_fmac_f32_e32 v7, v8, v4
	v_fma_f32 v3, -v3, v7, v6
	v_div_fmas_f32 v3, v3, v4, v7
	v_div_fixup_f32 v0, v3, v1, v0
	ds_write_b32 v2, v0
	v_add_u32_e32 v2, 0x800, v2
	s_waitcnt vmcnt(5)
	v_mov_b32_e32 v0, v82
	v_mul_f32_e32 v1, 0xbfb8aa3b, v0
	v_rndne_f32_e32 v4, v1
	v_fma_f32 v5, v0, s57, -v1
	v_sub_f32_e32 v1, v1, v4
	v_fmac_f32_e32 v5, 0xb2a5705f, v0
	v_add_f32_e32 v1, v1, v5
	v_cvt_i32_f32_e32 v4, v4
	v_exp_f32_e32 v1, v1
	v_cmp_nlt_f32_e64 s[0:1], s58, v0
	s_nop 0
	v_ldexp_f32 v1, v1, v4
	v_cndmask_b32_e64 v1, 0, v1, s[0:1]
	v_cmp_ngt_f32_e64 s[0:1], s59, v0
	s_nop 1
	v_cndmask_b32_e64 v1, v42, v1, s[0:1]
	v_add_f32_e32 v1, 1.0, v1
	v_div_scale_f32 v3, s[0:1], v1, v1, v0
	v_rcp_f32_e32 v4, v3
	v_div_scale_f32 v6, vcc, v0, v1, v0
	v_fma_f32 v7, -v3, v4, 1.0
	v_fmac_f32_e32 v4, v7, v4
	v_mul_f32_e32 v7, v6, v4
	v_fma_f32 v8, -v3, v7, v6
	v_fmac_f32_e32 v7, v8, v4
	v_fma_f32 v3, -v3, v7, v6
	v_div_fmas_f32 v3, v3, v4, v7
	v_div_fixup_f32 v0, v3, v1, v0
	ds_write_b32 v2, v0
	v_add_u32_e32 v2, 0x800, v2
	s_waitcnt vmcnt(4)
	v_mov_b32_e32 v0, v83
	v_mul_f32_e32 v1, 0xbfb8aa3b, v0
	v_rndne_f32_e32 v4, v1
	v_fma_f32 v5, v0, s57, -v1
	v_sub_f32_e32 v1, v1, v4
	v_fmac_f32_e32 v5, 0xb2a5705f, v0
	v_add_f32_e32 v1, v1, v5
	v_cvt_i32_f32_e32 v4, v4
	v_exp_f32_e32 v1, v1
	v_cmp_nlt_f32_e64 s[0:1], s58, v0
	s_nop 0
	v_ldexp_f32 v1, v1, v4
	v_cndmask_b32_e64 v1, 0, v1, s[0:1]
	v_cmp_ngt_f32_e64 s[0:1], s59, v0
	s_nop 1
	v_cndmask_b32_e64 v1, v42, v1, s[0:1]
	v_add_f32_e32 v1, 1.0, v1
	v_div_scale_f32 v3, s[0:1], v1, v1, v0
	v_rcp_f32_e32 v4, v3
	v_div_scale_f32 v6, vcc, v0, v1, v0
	v_fma_f32 v7, -v3, v4, 1.0
	v_fmac_f32_e32 v4, v7, v4
	v_mul_f32_e32 v7, v6, v4
	v_fma_f32 v8, -v3, v7, v6
	v_fmac_f32_e32 v7, v8, v4
	v_fma_f32 v3, -v3, v7, v6
	v_div_fmas_f32 v3, v3, v4, v7
	v_div_fixup_f32 v0, v3, v1, v0
	ds_write_b32 v2, v0
	v_add_u32_e32 v2, 0x800, v2
	s_waitcnt vmcnt(3)
	v_mov_b32_e32 v0, v84
	v_mul_f32_e32 v1, 0xbfb8aa3b, v0
	v_rndne_f32_e32 v4, v1
	v_fma_f32 v5, v0, s57, -v1
	v_sub_f32_e32 v1, v1, v4
	v_fmac_f32_e32 v5, 0xb2a5705f, v0
	v_add_f32_e32 v1, v1, v5
	v_cvt_i32_f32_e32 v4, v4
	v_exp_f32_e32 v1, v1
	v_cmp_nlt_f32_e64 s[0:1], s58, v0
	s_nop 0
	v_ldexp_f32 v1, v1, v4
	v_cndmask_b32_e64 v1, 0, v1, s[0:1]
	v_cmp_ngt_f32_e64 s[0:1], s59, v0
	s_nop 1
	v_cndmask_b32_e64 v1, v42, v1, s[0:1]
	v_add_f32_e32 v1, 1.0, v1
	v_div_scale_f32 v3, s[0:1], v1, v1, v0
	v_rcp_f32_e32 v4, v3
	v_div_scale_f32 v6, vcc, v0, v1, v0
	v_fma_f32 v7, -v3, v4, 1.0
	v_fmac_f32_e32 v4, v7, v4
	v_mul_f32_e32 v7, v6, v4
	v_fma_f32 v8, -v3, v7, v6
	v_fmac_f32_e32 v7, v8, v4
	v_fma_f32 v3, -v3, v7, v6
	v_div_fmas_f32 v3, v3, v4, v7
	v_div_fixup_f32 v0, v3, v1, v0
	ds_write_b32 v2, v0
	v_add_u32_e32 v2, 0x800, v2
	s_waitcnt vmcnt(2)
	v_mov_b32_e32 v0, v85
	v_mul_f32_e32 v1, 0xbfb8aa3b, v0
	v_rndne_f32_e32 v4, v1
	v_fma_f32 v5, v0, s57, -v1
	v_sub_f32_e32 v1, v1, v4
	v_fmac_f32_e32 v5, 0xb2a5705f, v0
	v_add_f32_e32 v1, v1, v5
	v_cvt_i32_f32_e32 v4, v4
	v_exp_f32_e32 v1, v1
	v_cmp_nlt_f32_e64 s[0:1], s58, v0
	s_nop 0
	v_ldexp_f32 v1, v1, v4
	v_cndmask_b32_e64 v1, 0, v1, s[0:1]
	v_cmp_ngt_f32_e64 s[0:1], s59, v0
	s_nop 1
	v_cndmask_b32_e64 v1, v42, v1, s[0:1]
	v_add_f32_e32 v1, 1.0, v1
	v_div_scale_f32 v3, s[0:1], v1, v1, v0
	v_rcp_f32_e32 v4, v3
	v_div_scale_f32 v6, vcc, v0, v1, v0
	v_fma_f32 v7, -v3, v4, 1.0
	v_fmac_f32_e32 v4, v7, v4
	v_mul_f32_e32 v7, v6, v4
	v_fma_f32 v8, -v3, v7, v6
	v_fmac_f32_e32 v7, v8, v4
	v_fma_f32 v3, -v3, v7, v6
	v_div_fmas_f32 v3, v3, v4, v7
	v_div_fixup_f32 v0, v3, v1, v0
	ds_write_b32 v2, v0
	v_add_u32_e32 v2, 0x800, v2
	s_waitcnt vmcnt(1)
	v_mov_b32_e32 v0, v86
	v_mul_f32_e32 v1, 0xbfb8aa3b, v0
	v_rndne_f32_e32 v4, v1
	v_fma_f32 v5, v0, s57, -v1
	v_sub_f32_e32 v1, v1, v4
	v_fmac_f32_e32 v5, 0xb2a5705f, v0
	v_add_f32_e32 v1, v1, v5
	v_cvt_i32_f32_e32 v4, v4
	v_exp_f32_e32 v1, v1
	v_cmp_nlt_f32_e64 s[0:1], s58, v0
	s_nop 0
	v_ldexp_f32 v1, v1, v4
	v_cndmask_b32_e64 v1, 0, v1, s[0:1]
	v_cmp_ngt_f32_e64 s[0:1], s59, v0
	s_nop 1
	v_cndmask_b32_e64 v1, v42, v1, s[0:1]
	v_add_f32_e32 v1, 1.0, v1
	v_div_scale_f32 v3, s[0:1], v1, v1, v0
	v_rcp_f32_e32 v4, v3
	v_div_scale_f32 v6, vcc, v0, v1, v0
	v_fma_f32 v7, -v3, v4, 1.0
	v_fmac_f32_e32 v4, v7, v4
	v_mul_f32_e32 v7, v6, v4
	v_fma_f32 v8, -v3, v7, v6
	v_fmac_f32_e32 v7, v8, v4
	v_fma_f32 v3, -v3, v7, v6
	v_div_fmas_f32 v3, v3, v4, v7
	v_div_fixup_f32 v0, v3, v1, v0
	ds_write_b32 v2, v0
	v_add_u32_e32 v2, 0x800, v2
	s_waitcnt vmcnt(0)
	v_mov_b32_e32 v0, v87
	v_mul_f32_e32 v1, 0xbfb8aa3b, v0
	v_rndne_f32_e32 v4, v1
	v_fma_f32 v5, v0, s57, -v1
	v_sub_f32_e32 v1, v1, v4
	v_fmac_f32_e32 v5, 0xb2a5705f, v0
	v_add_f32_e32 v1, v1, v5
	v_cvt_i32_f32_e32 v4, v4
	v_exp_f32_e32 v1, v1
	v_cmp_nlt_f32_e64 s[0:1], s58, v0
	s_nop 0
	v_ldexp_f32 v1, v1, v4
	v_cndmask_b32_e64 v1, 0, v1, s[0:1]
	v_cmp_ngt_f32_e64 s[0:1], s59, v0
	s_nop 1
	v_cndmask_b32_e64 v1, v42, v1, s[0:1]
	v_add_f32_e32 v1, 1.0, v1
	v_div_scale_f32 v3, s[0:1], v1, v1, v0
	v_rcp_f32_e32 v4, v3
	v_div_scale_f32 v6, vcc, v0, v1, v0
	v_fma_f32 v7, -v3, v4, 1.0
	v_fmac_f32_e32 v4, v7, v4
	v_mul_f32_e32 v7, v6, v4
	v_fma_f32 v8, -v3, v7, v6
	v_fmac_f32_e32 v7, v8, v4
	v_fma_f32 v3, -v3, v7, v6
	v_div_fmas_f32 v3, v3, v4, v7
	v_div_fixup_f32 v0, v3, v1, v0
	ds_write_b32 v2, v0
	v_add_u32_e32 v2, 0x800, v2
